# attention near-diagonal tiles: per-element bias read from a clamp-free padded LDS table straight into the S accumulators, same pipelined body as far tiles
# speedup vs baseline: 1.0302x; 1.0112x over previous
.LBB0_573:
	s_and_b64 vcc, exec, s[0:1]
	s_cbranch_vccz .LBB0_602
	s_mov_b64 s[58:59], s[94:95]
	s_mov_b64 s[46:47], s[94:95]
	s_mov_b64 s[42:43], s[94:95]
	s_mov_b64 s[34:35], s[94:95]
	s_mov_b64 s[0:1], s[94:95]
	s_add_u32 s0, s0, s76
	s_addc_u32 s1, s1, 0
	s_add_u32 s0, s0, 0x20000
	s_addc_u32 s1, s1, 0
	s_lshl_b32 s22, s77, 5
	s_and_b32 s22, s22, 0xf800
	s_add_i32 s40, s22, 0xffffb000
	s_lshl_b32 s22, s77, 7
	s_and_b32 s73, s22, 0x780
	s_or_b32 s36, s40, s73
	s_mov_b32 s37, s53
	s_bfe_u32 s3, s77, 0x20004
	s_lshl_b64 s[60:61], s[36:37], 10
	s_add_u32 s22, s58, s60
	v_mov_b32_e32 v18, v226
	s_addc_u32 s37, s59, s61
	s_lshl_b32 s41, s3, 8
	s_add_u32 s58, s22, s41
	v_lshlrev_b32_e32 v0, 4, v18
	v_add_u32_e32 v30, 0x200, v18
	v_add_u32_e32 v10, 0x400, v18
	v_add_u32_e32 v12, 0x600, v18
	s_addc_u32 s59, s37, 0
	v_and_b32_e32 v20, 0xf0, v0
	v_mov_b32_e32 v21, v177
	v_ashrrev_i32_e32 v22, 4, v18
	v_ashrrev_i32_e32 v24, 4, v30
	v_ashrrev_i32_e32 v26, 4, v10
	v_ashrrev_i32_e32 v28, 4, v12
	s_mul_i32 s22, s3, 0x208
	v_lshl_add_u64 v[0:1], s[58:59], 0, v[20:21]
	s_mov_b64 s[14:15], 0x8b00000
	v_ashrrev_i32_e32 v23, 31, v22
	v_ashrrev_i32_e32 v25, 31, v24
	v_ashrrev_i32_e32 v27, 31, v26
	v_ashrrev_i32_e32 v29, 31, v28
	v_add_u32_e32 v32, s22, v18
	v_lshl_add_u64 v[8:9], v[0:1], 0, s[14:15]
	v_lshlrev_b64 v[16:17], 10, v[22:23]
	v_lshlrev_b64 v[2:3], 10, v[24:25]
	v_lshlrev_b64 v[10:11], 10, v[26:27]
	v_lshlrev_b64 v[12:13], 10, v[28:29]
	v_ashrrev_i32_e32 v33, 31, v32
	v_lshl_add_u64 v[0:1], v[8:9], 0, v[16:17]
	v_lshl_add_u64 v[2:3], v[8:9], 0, v[2:3]
	v_lshl_add_u64 v[10:11], v[8:9], 0, v[10:11]
	v_lshl_add_u64 v[8:9], v[8:9], 0, v[12:13]
	v_lshl_add_u64 v[32:33], v[32:33], 2, s[0:1]
	flat_load_dwordx4 v[4:7], v[0:1]
	s_nop 0
	flat_load_dwordx4 v[0:3], v[2:3]
	s_nop 0
	flat_load_dwordx4 v[12:15], v[10:11]
	s_nop 0
	flat_load_dwordx4 v[8:11], v[8:9]
	v_readfirstlane_b32 s58, v18
	flat_load_dword v21, v[32:33]
	v_mov_b32_e32 v80, 0x100
	v_cmp_lt_u32_e32 vcc, 0x1c0, v18
	s_nop 1
	v_cndmask_b32_e64 v81, 0, 1, vcc
	v_mul_u32_u24_e32 v84, 0x1c1, v81
	v_sub_u32_e32 v82, v18, v84
	v_add_u32_e32 v82, 0xffffffa0, v82
	v_med3_i32 v82, v82, 0, v80
	v_mul_u32_u24_e32 v84, 0x104, v81
	v_add3_u32 v82, v82, v84, s22
	v_mov_b32_e32 v83, 0
	v_lshl_add_u64 v[82:83], v[82:83], 2, s[0:1]
	global_load_dword v88, v[82:83], off
	v_add_u32_e32 v85, 0x200, v18
	v_min_u32_e32 v85, 0x381, v85
	v_add_u32_e32 v86, 0xfffffddf, v85
	v_med3_i32 v86, v86, 0, v80
	v_add_u32_e32 v86, 0x104, v86
	v_add_u32_e32 v86, s22, v86
	v_mov_b32_e32 v87, 0
	v_lshl_add_u64 v[86:87], v[86:87], 2, s[0:1]
	global_load_dword v89, v[86:87], off
	v_cmp_gt_i32_e32 vcc, 8, v18
	v_mov_b32_e32 v19, 0
	v_mov_b32_e32 v25, 0
	s_and_saveexec_b64 s[68:69], vcc
	s_cbranch_execz .LBB0_576
	v_add_u32_e32 v30, s22, v30
	v_ashrrev_i32_e32 v31, 31, v30
	v_lshl_add_u64 v[30:31], v[30:31], 2, s[0:1]
	flat_load_dword v25, v[30:31]

.LBB0_578:
	s_or_b64 exec, exec, s[68:69]
	s_mov_b32 s41, s53
	s_lshl_b64 s[68:69], s[40:41], 10
	s_add_u32 s37, s46, s68
	s_addc_u32 s48, s47, s69
	s_lshl_b32 s3, s22, 1
	s_add_u32 s37, s37, s3
	s_addc_u32 s48, s48, 0
	s_add_u32 s60, s37, 0xab00000
	s_addc_u32 s61, s48, 0
	v_and_b32_e32 v27, 15, v18
	v_lshlrev_b64 v[32:33], 10, v[22:23]
	s_lshl_b32 s52, s22, 16
	v_lshlrev_b32_e32 v176, 4, v27
	v_lshl_add_u64 v[32:33], s[60:61], 0, v[32:33]
	s_add_u32 s37, s42, s52
	v_lshl_add_u64 v[36:37], v[32:33], 0, v[176:177]
	s_mov_b32 s7, 0x8000
	s_addc_u32 s48, s43, 0
	s_lshl_b64 s[70:71], s[40:41], 1
	v_ashrrev_i32_e32 v34, 3, v18
	v_lshl_add_u64 v[30:31], s[60:61], 0, v[16:17]
	v_add_co_u32_e64 v32, s[40:41], s7, v36
	s_add_u32 s62, s37, s70
	v_lshl_add_u64 v[30:31], v[30:31], 0, v[176:177]
	v_addc_co_u32_e64 v33, s[40:41], 0, v37, s[40:41]
	v_ashrrev_i32_e32 v35, 31, v34
	s_addc_u32 s63, s48, s71
	v_and_b32_e32 v29, 7, v18
	s_waitcnt vmcnt(0)
	flat_load_dwordx4 v[96:99], v[30:31]
	flat_load_dwordx4 v[100:103], v[32:33]
	v_lshlrev_b64 v[32:33], 16, v[34:35]
	v_lshl_add_u64 v[38:39], s[62:63], 0, v[32:33]
	v_lshlrev_b32_e32 v30, 4, v29
	v_mov_b32_e32 v31, v177
	v_lshl_add_u64 v[38:39], v[38:39], 0, v[30:31]
	s_mov_b32 s7, 0xcb00000
	s_mov_b64 s[14:15], 0xcb00000
	v_add_co_u32_e64 v42, s[40:41], s7, v38
	v_lshl_add_u64 v[40:41], v[38:39], 0, s[14:15]
	s_nop 0
	v_addc_co_u32_e64 v43, s[40:41], 0, v39, s[40:41]
	s_mov_b64 s[14:15], 0xcf00000
	s_mov_b32 s7, 0xcf00000
	v_lshl_add_u64 v[44:45], v[38:39], 0, s[14:15]
	v_add_co_u32_e64 v38, s[40:41], s7, v38
	v_readlane_b32 s7, v255, 23
	s_nop 0
	v_addc_co_u32_e64 v39, s[40:41], 0, v39, s[40:41]
	v_add_co_u32_e64 v46, s[40:41], s9, v36
	s_nop 1
	v_addc_co_u32_e64 v47, s[40:41], 0, v37, s[40:41]
	v_add_co_u32_e64 v36, s[40:41], s10, v36
	s_nop 1
	v_addc_co_u32_e64 v37, s[40:41], 0, v37, s[40:41]
	flat_load_dwordx4 v[104:107], v[46:47]
	flat_load_dwordx4 v[108:111], v[36:37]
	flat_load_dwordx4 v[120:123], v[42:43]
	flat_load_dwordx4 v[112:115], v[40:41] offset:128
	flat_load_dwordx4 v[124:127], v[38:39]
	flat_load_dwordx4 v[116:119], v[44:45] offset:128
	v_add_u32_e32 v36, s7, v20
	v_mul_lo_u32 v20, v22, s12
	v_add_u32_e32 v22, v36, v20
	s_waitcnt vmcnt(0) lgkmcnt(0)
	v_lshlrev_b32_e32 v84, 2, v18
	v_add_u32_e32 v84, 0x1ac00, v84
	ds_write_b32 v84, v88
	v_lshlrev_b32_e32 v85, 2, v85
	v_add_u32_e32 v85, 0x1ac00, v85
	ds_write_b32 v85, v89
	ds_write_b128 v22, v[4:7]
	v_mad_u64_u32 v[4:5], s[40:41], v24, s12, v[36:37]
	ds_write_b128 v4, v[0:3]
	v_mad_u64_u32 v[0:1], s[40:41], v26, s12, v[36:37]
	ds_write_b128 v0, v[12:15]
	v_mad_u64_u32 v[0:1], s[40:41], v28, s12, v[36:37]
	ds_write_b128 v0, v[8:11]
	v_lshl_add_u32 v0, v18, 2, 0
	v_add_u32_e32 v1, 0x11800, v0
	ds_write_b32 v1, v21
	s_and_saveexec_b64 s[40:41], vcc
	ds_write_b32 v1, v25 offset:2048
	s_or_b64 exec, exec, s[40:41]
	s_and_saveexec_b64 s[40:41], s[0:1]
	v_add_u32_e32 v0, 0x1a900, v0
	ds_write_b32 v0, v19
	s_or_b64 exec, exec, s[40:41]
	s_ashr_i32 s60, s58, 8
	s_lshl_b32 s0, s60, 7
	s_bfe_u32 s61, s58, 0x20006
	s_add_i32 s1, s0, 0
	v_and_b32_e32 v2, 31, v18
	s_lshl_b32 s37, s61, 5
	s_add_i32 s1, s1, 0x12100
	v_or_b32_e32 v1, s37, v2
	v_mov_b32_e32 v3, s1
	v_lshlrev_b32_e32 v0, 3, v18
	v_mad_u32_u24 v3, v1, s12, v3
	v_add_u32_e32 v1, 0, v20
	s_movk_i32 s1, 0x90
	v_and_b32_e32 v0, 8, v0
	v_add_u32_e32 v239, v1, v176
	v_mul_lo_u32 v1, v34, s1
	v_and_or_b32 v0, v30, s8, v0
	v_add_u32_e32 v1, 0, v1
	v_add_u32_e32 v240, v1, v0
	s_mul_i32 s1, s60, 0x410
	v_mad_u32_u24 v0, v2, s12, 0
	s_add_i32 s62, s1, 0
	s_or_b32 s72, s37, s73
	v_add_u32_e32 v4, s0, v0
	s_lshl_b32 s0, s77, 4
	s_lshr_b32 s59, s58, 6
	s_add_i32 s62, s62, 0x11800
	s_add_i32 s63, s72, 0x9f
	s_addk_i32 s72, 0x5f
	s_and_b32 s0, s0, 0x300
	v_bfe_u32 v236, v18, 5, 1
	v_lshlrev_b32_e32 v1, 7, v2
	s_add_u32 s0, s0, s68
	v_lshlrev_b32_e32 v237, 4, v236
	v_sub_u32_e32 v0, v0, v1
	s_addc_u32 s1, 0, s69
	v_add_u32_e32 v243, v0, v237
	v_lshl_add_u64 v[0:1], s[0:1], 0, v[16:17]
	v_lshl_add_u64 v[0:1], v[0:1], 0, v[176:177]
	v_lshl_add_u64 v[0:1], s[46:47], 0, v[0:1]
	s_mov_b64 s[0:1], 0xab38000
	v_lshl_add_u64 v[190:191], v[0:1], 0, s[0:1]
	v_lshl_add_u64 v[0:1], s[52:53], 0, v[32:33]
	v_mov_b32_e32 v31, v177
	s_add_u32 s0, s42, s70
	v_lshl_add_u64 v[0:1], v[0:1], 0, v[30:31]
	s_addc_u32 s1, s43, s71
	v_lshlrev_b32_e32 v235, 2, v236
	v_lshl_add_u64 v[0:1], s[0:1], 0, v[0:1]
	s_mov_b64 s[0:1], 0xcf00180
	v_lshl_add_u64 v[192:193], v[0:1], 0, s[0:1]
	v_sub_u32_e32 v0, v235, v2
	v_subrev_u32_e32 v0, s37, v0
	s_add_i32 s0, s37, s73
	v_mov_b32_e32 v248, 0
	v_lshlrev_b32_e32 v233, 3, v27
	v_and_b32_e32 v234, 63, v18
	v_add_u32_e32 v241, 0x8800, v240
	v_add_u32_e32 v242, 0xa800, v240
	v_mul_u32_u24_e32 v238, 0x110, v2
	v_add_u32_e32 v244, 0xd000, v243
	v_subrev_u32_e32 v245, s73, v0
	s_mov_b32 s22, 0
	s_sub_i32 s46, 0, s0
	v_add_u32_e32 v246, v4, v237
	v_add_u32_e32 v247, v3, v237
	s_mov_b32 s47, 0
	v_mov_b32_e32 v0, 0
	v_mov_b32_e32 v1, v248
	v_mov_b32_e32 v2, v248
	v_mov_b32_e32 v3, v248
	v_mov_b32_e32 v4, v248
	v_mov_b32_e32 v5, v248
	v_mov_b32_e32 v6, v248
	v_mov_b32_e32 v7, v248
	v_mov_b32_e32 v8, v248
	v_mov_b32_e32 v9, v248
	v_mov_b32_e32 v10, v248
	v_mov_b32_e32 v11, v248
	v_mov_b32_e32 v12, v248
	v_mov_b32_e32 v13, v248
	v_mov_b32_e32 v14, v248
	v_mov_b32_e32 v15, v248
	v_mov_b32_e32 v16, 0
	v_mov_b32_e32 v17, v248
	v_mov_b32_e32 v18, v248
	v_mov_b32_e32 v19, v248
	v_mov_b32_e32 v20, v248
	v_mov_b32_e32 v21, v248
	v_mov_b32_e32 v22, v248
	v_mov_b32_e32 v23, v248
	v_mov_b32_e32 v24, v248
	v_mov_b32_e32 v25, v248
	v_mov_b32_e32 v26, v248
	v_mov_b32_e32 v27, v248
	v_mov_b32_e32 v28, v248
	v_mov_b32_e32 v29, v248
	v_mov_b32_e32 v30, v248
	v_mov_b32_e32 v31, v248
	v_mov_b32_e32 v32, 0
	v_mov_b32_e32 v33, v248
	v_mov_b32_e32 v34, v248
	v_mov_b32_e32 v35, v248
	v_mov_b32_e32 v36, v248
	v_mov_b32_e32 v37, v248
	v_mov_b32_e32 v38, v248
	v_mov_b32_e32 v39, v248
	v_mov_b32_e32 v40, v248
	v_mov_b32_e32 v41, v248
	v_mov_b32_e32 v42, v248
	v_mov_b32_e32 v43, v248
	v_mov_b32_e32 v44, v248
	v_mov_b32_e32 v45, v248
	v_mov_b32_e32 v46, v248
	v_mov_b32_e32 v47, v248
	v_mov_b32_e32 v48, 0
	v_mov_b32_e32 v49, v248
	v_mov_b32_e32 v50, v248
	v_mov_b32_e32 v51, v248
	v_mov_b32_e32 v52, v248
	v_mov_b32_e32 v53, v248
	v_mov_b32_e32 v54, v248
	v_mov_b32_e32 v55, v248
	v_mov_b32_e32 v56, v248
	v_mov_b32_e32 v57, v248
	v_mov_b32_e32 v58, v248
	v_mov_b32_e32 v59, v248
	v_mov_b32_e32 v60, v248
	v_mov_b32_e32 v61, v248
	v_mov_b32_e32 v62, v248
	v_mov_b32_e32 v63, v248
	ds_write_b128 v239, v[96:99]
	ds_write_b128 v239, v[100:103] offset:8704
	ds_write2_b64 v241, v[120:121], v[122:123] offset1:2
	ds_write2_b64 v242, v[124:125], v[126:127] offset0:128 offset1:130
	s_waitcnt lgkmcnt(0)
	s_barrier
	ds_read_b128 v[222:225], v247
	ds_read_b128 v[218:221], v247 offset:32
	ds_read_b128 v[214:217], v247 offset:64
	ds_read_b128 v[210:213], v247 offset:96
	s_mov_b32 s100, -1
	s_branch .LBB0_584

.La1t0_near:
	v_add_u32_e32 v249, s22, v245
	s_mul_i32 s101, s60, 0x704
	s_add_i32 s101, s101, 0x1af80
	v_lshl_add_u32 v251, v249, 2, s101
	ds_read_b32 v64, v251 offset:0
	ds_read_b32 v65, v251 offset:4
	ds_read_b32 v66, v251 offset:8
	ds_read_b32 v67, v251 offset:12
	ds_read_b32 v68, v251 offset:32
	ds_read_b32 v69, v251 offset:36
	ds_read_b32 v70, v251 offset:40
	ds_read_b32 v71, v251 offset:44
	ds_read_b32 v72, v251 offset:64
	ds_read_b32 v73, v251 offset:68
	ds_read_b32 v74, v251 offset:72
	ds_read_b32 v75, v251 offset:76
	ds_read_b32 v76, v251 offset:96
	ds_read_b32 v77, v251 offset:100
	ds_read_b32 v78, v251 offset:104
	ds_read_b32 v79, v251 offset:108
	ds_read_b32 v80, v251 offset:128
	ds_read_b32 v81, v251 offset:132
	ds_read_b32 v82, v251 offset:136
	ds_read_b32 v83, v251 offset:140
	ds_read_b32 v84, v251 offset:160
	ds_read_b32 v85, v251 offset:164
	ds_read_b32 v86, v251 offset:168
	ds_read_b32 v87, v251 offset:172
	ds_read_b32 v88, v251 offset:192
	ds_read_b32 v89, v251 offset:196
	ds_read_b32 v90, v251 offset:200
	ds_read_b32 v91, v251 offset:204
	ds_read_b32 v92, v251 offset:224
	ds_read_b32 v93, v251 offset:228
	ds_read_b32 v94, v251 offset:232
	ds_read_b32 v95, v251 offset:236
	s_waitcnt lgkmcnt(0)
	ds_read_b128 v[128:131], v243 offset:44032
	ds_read_b128 v[132:135], v243 offset:44064
	ds_read_b128 v[136:139], v243 offset:48640
	ds_read_b128 v[140:143], v243 offset:48672
	s_cmp_eq_u64 s[40:41], 0
	v_mfma_f32_32x32x16_bf16 v[64:79], v[172:175], v[222:225], v[64:79]
	s_cbranch_scc1 .La1t0n_nl0
	v_add_co_u32_e32 v186, vcc, 0xfffe8000, v190
	s_nop 1
	v_addc_co_u32_e32 v187, vcc, -1, v191, vcc
	global_load_dwordx4 v[96:99], v[186:187], off
.La1t0n_nl0:
	v_mfma_f32_32x32x16_bf16 v[64:79], v[168:171], v[218:221], v[64:79]
	s_cbranch_scc1 .La1t0n_nl1
	v_add_co_u32_e32 v186, vcc, 0xffff0000, v190
	s_nop 1
	v_addc_co_u32_e32 v187, vcc, -1, v191, vcc
	global_load_dwordx4 v[100:103], v[186:187], off
.La1t0n_nl1:
	v_mfma_f32_32x32x16_bf16 v[64:79], v[164:167], v[214:217], v[64:79]
	s_cbranch_scc1 .La1t0n_nl2
	v_add_co_u32_e32 v186, vcc, 0xffbfff80, v192
	s_nop 1
	v_addc_co_u32_e32 v187, vcc, -1, v193, vcc
	global_load_dwordx4 v[120:123], v[186:187], off
.La1t0n_nl2:
	v_mfma_f32_32x32x16_bf16 v[64:79], v[160:163], v[210:213], v[64:79]
	s_cbranch_scc1 .La1t0n_nl3
	v_add_co_u32_e32 v186, vcc, 0xffffff80, v192
	s_nop 1
	v_addc_co_u32_e32 v187, vcc, -1, v193, vcc
	global_load_dwordx4 v[124:127], v[186:187], off
.La1t0n_nl3:
	v_mfma_f32_32x32x16_bf16 v[80:95], v[156:159], v[222:225], v[80:95]
	s_nop 11
	v_exp_f32_e32 v64, v64
	v_exp_f32_e32 v65, v65
	v_exp_f32_e32 v66, v66
	v_exp_f32_e32 v67, v67
	v_exp_f32_e32 v68, v68
	v_exp_f32_e32 v69, v69
	v_mfma_f32_32x32x16_bf16 v[80:95], v[152:155], v[218:221], v[80:95]
	v_exp_f32_e32 v70, v70
	v_exp_f32_e32 v71, v71
	v_exp_f32_e32 v72, v72
	v_exp_f32_e32 v73, v73
	v_exp_f32_e32 v74, v74
	v_exp_f32_e32 v75, v75
	v_mfma_f32_32x32x16_bf16 v[80:95], v[148:151], v[214:217], v[80:95]
	v_exp_f32_e32 v76, v76
	v_exp_f32_e32 v77, v77
	v_exp_f32_e32 v78, v78
	v_exp_f32_e32 v79, v79
	v_cvt_pk_bf16_f32 v160, v64, v65
	v_cvt_pk_bf16_f32 v161, v66, v67
	v_mfma_f32_32x32x16_bf16 v[80:95], v[144:147], v[210:213], v[80:95]
	ds_read_b128 v[144:147], v243 offset:34816
	ds_read_b128 v[148:151], v243 offset:34848
	ds_read_b128 v[152:155], v243 offset:39424
	ds_read_b128 v[156:159], v243 offset:39456
	v_cvt_pk_bf16_f32 v162, v68, v69
	v_cvt_pk_bf16_f32 v163, v70, v71
	v_cvt_pk_bf16_f32 v164, v72, v73
	v_cvt_pk_bf16_f32 v165, v74, v75
	v_cvt_pk_bf16_f32 v166, v76, v77
	v_cvt_pk_bf16_f32 v167, v78, v79
	s_nop 4
	v_exp_f32_e32 v80, v80
	v_exp_f32_e32 v81, v81
	v_exp_f32_e32 v82, v82
	v_exp_f32_e32 v83, v83
	s_waitcnt lgkmcnt(7)
	v_mfma_f32_32x32x16_bf16 v[16:31], v[128:131], v[160:163], v[16:31]
	s_cmp_eq_u64 s[40:41], 0
	s_cbranch_scc1 .La1t0n_lv_a
	s_waitcnt vmcnt(4)
	s_branch .La1t0n_lv_b

.La1t0n_lv_b:
	v_add_u32_e32 v251, 0xd000, v240
	ds_write_b128 v239, v[104:107] offset:17408
	ds_write_b128 v239, v[108:111] offset:26112
	ds_write2_b64 v251, v[112:113], v[114:115] offset1:2
	v_add_u32_e32 v251, 0xf000, v240
	ds_write2_b64 v251, v[116:117], v[118:119] offset0:128 offset1:130
	v_exp_f32_e32 v84, v84
	v_exp_f32_e32 v85, v85
	v_exp_f32_e32 v86, v86
	s_waitcnt lgkmcnt(6)
	v_mfma_f32_32x32x16_bf16 v[16:31], v[132:135], v[164:167], v[16:31]
	ds_read_b128 v[128:131], v243 offset:44096
	ds_read_b128 v[132:135], v243 offset:44128
	v_exp_f32_e32 v87, v87
	v_exp_f32_e32 v88, v88
	v_exp_f32_e32 v89, v89
	s_waitcnt lgkmcnt(7)
	v_mfma_f32_32x32x16_bf16 v[0:15], v[136:139], v[160:163], v[0:15]
	v_exp_f32_e32 v90, v90
	v_exp_f32_e32 v91, v91
	v_exp_f32_e32 v92, v92
	s_waitcnt lgkmcnt(6)
	v_mfma_f32_32x32x16_bf16 v[0:15], v[140:143], v[164:167], v[0:15]
	ds_read_b128 v[136:139], v243 offset:48704
	ds_read_b128 v[140:143], v243 offset:48736
	v_exp_f32_e32 v93, v93
	v_exp_f32_e32 v94, v94
	v_exp_f32_e32 v95, v95
	s_waitcnt lgkmcnt(7)
	v_mfma_f32_32x32x16_bf16 v[48:63], v[144:147], v[160:163], v[48:63]
	v_cvt_pk_bf16_f32 v168, v80, v81
	v_cvt_pk_bf16_f32 v169, v82, v83
	s_waitcnt lgkmcnt(6)
	v_mfma_f32_32x32x16_bf16 v[48:63], v[148:151], v[164:167], v[48:63]
	ds_read_b128 v[144:147], v243 offset:34880
	ds_read_b128 v[148:151], v243 offset:34912
	v_cvt_pk_bf16_f32 v170, v84, v85
	v_cvt_pk_bf16_f32 v171, v86, v87
	s_waitcnt lgkmcnt(7)
	v_mfma_f32_32x32x16_bf16 v[32:47], v[152:155], v[160:163], v[32:47]
	v_cvt_pk_bf16_f32 v172, v88, v89
	v_cvt_pk_bf16_f32 v173, v90, v91
	s_waitcnt lgkmcnt(6)
	v_mfma_f32_32x32x16_bf16 v[32:47], v[156:159], v[164:167], v[32:47]
	ds_read_b128 v[152:155], v243 offset:39488
	ds_read_b128 v[156:159], v243 offset:39520
	v_cvt_pk_bf16_f32 v174, v92, v93
	v_cvt_pk_bf16_f32 v175, v94, v95
	s_nop 1
	s_waitcnt lgkmcnt(7)
	v_mfma_f32_32x32x16_bf16 v[16:31], v[128:131], v[168:171], v[16:31]
	v_add_f32_e32 v186, v64, v67
	v_add_f32_e32 v187, v65, v68
	v_add_f32_e32 v251, v66, v69
	v_add_f32_e32 v186, v186, v70
	v_add_f32_e32 v187, v187, v71
	s_waitcnt lgkmcnt(6)
	v_mfma_f32_32x32x16_bf16 v[16:31], v[132:135], v[172:175], v[16:31]
	v_add_f32_e32 v251, v251, v72
	v_add_f32_e32 v186, v186, v73
	v_add_f32_e32 v187, v187, v74
	v_add_f32_e32 v251, v251, v75
	v_add_f32_e32 v186, v186, v76
	s_waitcnt lgkmcnt(5)
	v_mfma_f32_32x32x16_bf16 v[0:15], v[136:139], v[168:171], v[0:15]
	v_add_f32_e32 v187, v187, v77
	v_add_f32_e32 v251, v251, v78
	v_add_f32_e32 v186, v186, v79
	v_add_f32_e32 v187, v187, v80
	v_add_f32_e32 v251, v251, v81
	s_waitcnt lgkmcnt(4)
	v_mfma_f32_32x32x16_bf16 v[0:15], v[140:143], v[172:175], v[0:15]
	v_add_f32_e32 v186, v186, v82
	v_add_f32_e32 v187, v187, v83
	v_add_f32_e32 v251, v251, v84
	v_add_f32_e32 v186, v186, v85
	v_add_f32_e32 v187, v187, v86
	s_waitcnt lgkmcnt(3)
	v_mfma_f32_32x32x16_bf16 v[48:63], v[144:147], v[168:171], v[48:63]
	v_add_f32_e32 v251, v251, v87
	v_add_f32_e32 v186, v186, v88
	v_add_f32_e32 v187, v187, v89
	v_add_f32_e32 v251, v251, v90
	v_add_f32_e32 v186, v186, v91
	s_waitcnt lgkmcnt(2)
	v_mfma_f32_32x32x16_bf16 v[48:63], v[148:151], v[172:175], v[48:63]
	v_add_f32_e32 v187, v187, v92
	v_add_f32_e32 v251, v251, v93
	v_add_f32_e32 v186, v186, v94
	v_add_f32_e32 v187, v187, v95
	v_add_f32_e32 v186, v186, v187
	s_waitcnt lgkmcnt(1)
	v_mfma_f32_32x32x16_bf16 v[32:47], v[152:155], v[168:171], v[32:47]
	v_add_f32_e32 v186, v186, v251
	v_add_f32_e32 v248, v248, v186
	s_waitcnt lgkmcnt(0)
	v_mfma_f32_32x32x16_bf16 v[32:47], v[156:159], v[172:175], v[32:47]
	s_setprio 0
	s_branch .La1t0_pw
.LBB0_588:
	v_add_u32_e32 v249, s22, v245

.La1t1_near:
	s_mul_i32 s101, s60, 0x704
	s_add_i32 s101, s101, 0x1b080
	v_lshl_add_u32 v251, v249, 2, s101
	ds_read_b32 v64, v251 offset:0
	ds_read_b32 v65, v251 offset:4
	ds_read_b32 v66, v251 offset:8
	ds_read_b32 v67, v251 offset:12
	ds_read_b32 v68, v251 offset:32
	ds_read_b32 v69, v251 offset:36
	ds_read_b32 v70, v251 offset:40
	ds_read_b32 v71, v251 offset:44
	ds_read_b32 v72, v251 offset:64
	ds_read_b32 v73, v251 offset:68
	ds_read_b32 v74, v251 offset:72
	ds_read_b32 v75, v251 offset:76
	ds_read_b32 v76, v251 offset:96
	ds_read_b32 v77, v251 offset:100
	ds_read_b32 v78, v251 offset:104
	ds_read_b32 v79, v251 offset:108
	ds_read_b32 v80, v251 offset:128
	ds_read_b32 v81, v251 offset:132
	ds_read_b32 v82, v251 offset:136
	ds_read_b32 v83, v251 offset:140
	ds_read_b32 v84, v251 offset:160
	ds_read_b32 v85, v251 offset:164
	ds_read_b32 v86, v251 offset:168
	ds_read_b32 v87, v251 offset:172
	ds_read_b32 v88, v251 offset:192
	ds_read_b32 v89, v251 offset:196
	ds_read_b32 v90, v251 offset:200
	ds_read_b32 v91, v251 offset:204
	ds_read_b32 v92, v251 offset:224
	ds_read_b32 v93, v251 offset:228
	ds_read_b32 v94, v251 offset:232
	ds_read_b32 v95, v251 offset:236
	s_waitcnt lgkmcnt(0)
	ds_read_b128 v[128:131], v243 offset:62464
	ds_read_b128 v[132:135], v243 offset:62496
	ds_read_b128 v[136:139], v244 offset:13824
	ds_read_b128 v[140:143], v244 offset:13856
	s_cmp_eq_u64 s[40:41], 0
	v_mfma_f32_32x32x16_bf16 v[64:79], v[172:175], v[222:225], v[64:79]
	s_cbranch_scc1 .La1t1n_nl0
	v_add_co_u32_e32 v186, vcc, 0xffff8000, v190
	s_nop 1
	v_addc_co_u32_e32 v187, vcc, -1, v191, vcc
	global_load_dwordx4 v[104:107], v[186:187], off
.La1t1n_nl0:
	v_mfma_f32_32x32x16_bf16 v[64:79], v[168:171], v[218:221], v[64:79]
	s_cbranch_scc1 .La1t1n_nl1
	global_load_dwordx4 v[108:111], v[190:191], off
.La1t1n_nl1:
	v_mfma_f32_32x32x16_bf16 v[64:79], v[164:167], v[214:217], v[64:79]
	s_cbranch_scc1 .La1t1n_nl2
	v_add_co_u32_e32 v186, vcc, 0xffc00000, v192
	s_nop 1
	v_addc_co_u32_e32 v187, vcc, -1, v193, vcc
	global_load_dwordx4 v[112:115], v[186:187], off
.La1t1n_nl2:
	v_mfma_f32_32x32x16_bf16 v[64:79], v[160:163], v[210:213], v[64:79]
	s_cbranch_scc1 .La1t1n_nl3
	global_load_dwordx4 v[116:119], v[192:193], off
.La1t1n_nl3:
	v_mfma_f32_32x32x16_bf16 v[80:95], v[156:159], v[222:225], v[80:95]
	s_nop 11
	v_exp_f32_e32 v64, v64
	v_exp_f32_e32 v65, v65
	v_exp_f32_e32 v66, v66
	v_exp_f32_e32 v67, v67
	v_exp_f32_e32 v68, v68
	v_exp_f32_e32 v69, v69
	v_mfma_f32_32x32x16_bf16 v[80:95], v[152:155], v[218:221], v[80:95]
	v_exp_f32_e32 v70, v70
	v_exp_f32_e32 v71, v71
	v_exp_f32_e32 v72, v72
	v_exp_f32_e32 v73, v73
	v_exp_f32_e32 v74, v74
	v_exp_f32_e32 v75, v75
	v_mfma_f32_32x32x16_bf16 v[80:95], v[148:151], v[214:217], v[80:95]
	v_exp_f32_e32 v76, v76
	v_exp_f32_e32 v77, v77
	v_exp_f32_e32 v78, v78
	v_exp_f32_e32 v79, v79
	v_cvt_pk_bf16_f32 v160, v64, v65
	v_cvt_pk_bf16_f32 v161, v66, v67
	v_mfma_f32_32x32x16_bf16 v[80:95], v[144:147], v[210:213], v[80:95]
	ds_read_b128 v[144:147], v243 offset:53248
	ds_read_b128 v[148:151], v243 offset:53280
	ds_read_b128 v[152:155], v243 offset:57856
	ds_read_b128 v[156:159], v243 offset:57888
	v_cvt_pk_bf16_f32 v162, v68, v69
	v_cvt_pk_bf16_f32 v163, v70, v71
	v_cvt_pk_bf16_f32 v164, v72, v73
	v_cvt_pk_bf16_f32 v165, v74, v75
	v_cvt_pk_bf16_f32 v166, v76, v77
	v_cvt_pk_bf16_f32 v167, v78, v79
	s_nop 4
	v_exp_f32_e32 v80, v80
	v_exp_f32_e32 v81, v81
	v_exp_f32_e32 v82, v82
	v_exp_f32_e32 v83, v83
	s_waitcnt lgkmcnt(7)
	v_mfma_f32_32x32x16_bf16 v[16:31], v[128:131], v[160:163], v[16:31]
	s_cmp_eq_u64 s[40:41], 0
	s_cbranch_scc1 .La1t1n_lv_s
	s_waitcnt vmcnt(4)
	ds_write_b128 v239, v[96:99]
	ds_write_b128 v239, v[100:103] offset:8704
	ds_write2_b64 v241, v[120:121], v[122:123] offset1:2
	ds_write2_b64 v242, v[124:125], v[126:127] offset0:128 offset1:130
.La1t1n_lv_s:
	v_exp_f32_e32 v84, v84
	v_exp_f32_e32 v85, v85
	v_exp_f32_e32 v86, v86
	s_waitcnt lgkmcnt(6)
	v_mfma_f32_32x32x16_bf16 v[16:31], v[132:135], v[164:167], v[16:31]
	ds_read_b128 v[128:131], v243 offset:62528
	ds_read_b128 v[132:135], v243 offset:62560
	v_exp_f32_e32 v87, v87
	v_exp_f32_e32 v88, v88
	v_exp_f32_e32 v89, v89
	s_waitcnt lgkmcnt(7)
	v_mfma_f32_32x32x16_bf16 v[0:15], v[136:139], v[160:163], v[0:15]
	v_exp_f32_e32 v90, v90
	v_exp_f32_e32 v91, v91
	v_exp_f32_e32 v92, v92
	s_waitcnt lgkmcnt(6)
	v_mfma_f32_32x32x16_bf16 v[0:15], v[140:143], v[164:167], v[0:15]
	ds_read_b128 v[136:139], v244 offset:13888
	ds_read_b128 v[140:143], v244 offset:13920
	v_exp_f32_e32 v93, v93
	v_exp_f32_e32 v94, v94
	v_exp_f32_e32 v95, v95
	s_waitcnt lgkmcnt(7)
	v_mfma_f32_32x32x16_bf16 v[48:63], v[144:147], v[160:163], v[48:63]
	v_cvt_pk_bf16_f32 v168, v80, v81
	v_cvt_pk_bf16_f32 v169, v82, v83
	s_waitcnt lgkmcnt(6)
	v_mfma_f32_32x32x16_bf16 v[48:63], v[148:151], v[164:167], v[48:63]
	ds_read_b128 v[144:147], v243 offset:53312
	ds_read_b128 v[148:151], v243 offset:53344
	v_cvt_pk_bf16_f32 v170, v84, v85
	v_cvt_pk_bf16_f32 v171, v86, v87
	s_waitcnt lgkmcnt(7)
	v_mfma_f32_32x32x16_bf16 v[32:47], v[152:155], v[160:163], v[32:47]
	v_cvt_pk_bf16_f32 v172, v88, v89
	v_cvt_pk_bf16_f32 v173, v90, v91
	s_waitcnt lgkmcnt(6)
	v_mfma_f32_32x32x16_bf16 v[32:47], v[156:159], v[164:167], v[32:47]
	ds_read_b128 v[152:155], v243 offset:57920
	ds_read_b128 v[156:159], v243 offset:57952
	v_cvt_pk_bf16_f32 v174, v92, v93
	v_cvt_pk_bf16_f32 v175, v94, v95
	s_nop 1
	s_waitcnt lgkmcnt(7)
	v_mfma_f32_32x32x16_bf16 v[16:31], v[128:131], v[168:171], v[16:31]
	v_add_f32_e32 v186, v64, v67
	v_add_f32_e32 v187, v65, v68
	v_add_f32_e32 v251, v66, v69
	v_add_f32_e32 v186, v186, v70
	v_add_f32_e32 v187, v187, v71
	s_waitcnt lgkmcnt(6)
	v_mfma_f32_32x32x16_bf16 v[16:31], v[132:135], v[172:175], v[16:31]
	v_add_f32_e32 v251, v251, v72
	v_add_f32_e32 v186, v186, v73
	v_add_f32_e32 v187, v187, v74
	v_add_f32_e32 v251, v251, v75
	v_add_f32_e32 v186, v186, v76
	s_waitcnt lgkmcnt(5)
	v_mfma_f32_32x32x16_bf16 v[0:15], v[136:139], v[168:171], v[0:15]
	v_add_f32_e32 v187, v187, v77
	v_add_f32_e32 v251, v251, v78
	v_add_f32_e32 v186, v186, v79
	v_add_f32_e32 v187, v187, v80
	v_add_f32_e32 v251, v251, v81
	s_waitcnt lgkmcnt(4)
	v_mfma_f32_32x32x16_bf16 v[0:15], v[140:143], v[172:175], v[0:15]
	v_add_f32_e32 v186, v186, v82
	v_add_f32_e32 v187, v187, v83
	v_add_f32_e32 v251, v251, v84
	v_add_f32_e32 v186, v186, v85
	v_add_f32_e32 v187, v187, v86
	s_waitcnt lgkmcnt(3)
	v_mfma_f32_32x32x16_bf16 v[48:63], v[144:147], v[168:171], v[48:63]
	v_add_f32_e32 v251, v251, v87
	v_add_f32_e32 v186, v186, v88
	v_add_f32_e32 v187, v187, v89
	v_add_f32_e32 v251, v251, v90
	v_add_f32_e32 v186, v186, v91
	s_waitcnt lgkmcnt(2)
	v_mfma_f32_32x32x16_bf16 v[48:63], v[148:151], v[172:175], v[48:63]
	v_add_f32_e32 v187, v187, v92
	v_add_f32_e32 v251, v251, v93
	v_add_f32_e32 v186, v186, v94
	v_add_f32_e32 v187, v187, v95
	v_add_f32_e32 v186, v186, v187
	s_waitcnt lgkmcnt(1)
	v_mfma_f32_32x32x16_bf16 v[32:47], v[152:155], v[168:171], v[32:47]
	v_add_f32_e32 v186, v186, v251
	v_add_f32_e32 v248, v248, v186
	s_waitcnt lgkmcnt(0)
	v_mfma_f32_32x32x16_bf16 v[32:47], v[156:159], v[172:175], v[32:47]
	s_setprio 0
	s_branch .LBB0_583
.LBB0_594:
.LBB0_595:
	s_nop 9
	v_add_u32_e32 v88, 0xc0, v249
	v_max_i32_e32 v65, -1, v88
	v_max_i32_e32 v66, -2, v88
	v_max_i32_e32 v67, -3, v88
	v_max_i32_e32 v68, -8, v88
	v_max_i32_e32 v69, -9, v88
	v_max_i32_e32 v70, -10, v88
	v_max_i32_e32 v71, -11, v88
	v_max_i32_e32 v72, -16, v88
	v_max_i32_e32 v73, 0xffffffef, v88
	v_max_i32_e32 v74, 0xffffffee, v88
	v_max_i32_e32 v75, 0xffffffed, v88
	v_max_i32_e32 v76, 0xffffffe8, v88
	v_max_i32_e32 v77, 0xffffffe7, v88
	v_max_i32_e32 v78, 0xffffffe6, v88
	v_max_i32_e32 v79, 0xffffffe5, v88
	v_add_u32_e32 v65, 1, v65
	v_add_u32_e32 v66, 2, v66
	v_add_u32_e32 v67, 3, v67
	v_add_u32_e32 v68, 8, v68
	v_add_u32_e32 v69, 9, v69
	v_add_u32_e32 v70, 10, v70
	v_add_u32_e32 v71, 11, v71
	v_add_u32_e32 v72, 16, v72
	v_add_u32_e32 v73, 17, v73
	v_add_u32_e32 v74, 18, v74
	v_add_u32_e32 v75, 19, v75
	v_add_u32_e32 v76, 24, v76
	v_add_u32_e32 v77, 25, v77
	v_add_u32_e32 v78, 26, v78
	v_add_u32_e32 v79, 27, v79
	v_med3_i32 v64, v88, 0, v232
	v_min_u32_e32 v65, 0x100, v65
	v_min_u32_e32 v66, 0x100, v66
	v_min_u32_e32 v67, 0x100, v67
	v_min_u32_e32 v68, 0x100, v68
	v_min_u32_e32 v69, 0x100, v69
	v_min_u32_e32 v70, 0x100, v70
	v_min_u32_e32 v71, 0x100, v71
	v_min_u32_e32 v72, 0x100, v72
	v_min_u32_e32 v73, 0x100, v73
	v_min_u32_e32 v74, 0x100, v74
	v_min_u32_e32 v75, 0x100, v75
	v_min_u32_e32 v76, 0x100, v76
	v_min_u32_e32 v77, 0x100, v77
	v_min_u32_e32 v78, 0x100, v78
	v_min_u32_e32 v79, 0x100, v79
	v_lshl_add_u32 v64, v64, 2, s62
	v_lshl_add_u32 v65, v65, 2, s62
	v_lshl_add_u32 v66, v66, 2, s62
	v_lshl_add_u32 v67, v67, 2, s62
	v_lshl_add_u32 v68, v68, 2, s62
	v_lshl_add_u32 v69, v69, 2, s62
	v_lshl_add_u32 v70, v70, 2, s62
	v_lshl_add_u32 v71, v71, 2, s62
	v_lshl_add_u32 v72, v72, 2, s62
	v_lshl_add_u32 v73, v73, 2, s62
	v_lshl_add_u32 v74, v74, 2, s62
	v_lshl_add_u32 v75, v75, 2, s62
	v_lshl_add_u32 v76, v76, 2, s62
	v_lshl_add_u32 v77, v77, 2, s62
	v_lshl_add_u32 v78, v78, 2, s62
	v_lshl_add_u32 v79, v79, 2, s62
	ds_read_b32 v64, v64
	ds_read_b32 v65, v65
	ds_read_b32 v66, v66
	ds_read_b32 v67, v67
	ds_read_b32 v68, v68
	ds_read_b32 v69, v69
	ds_read_b32 v70, v70
	ds_read_b32 v71, v71
	ds_read_b32 v72, v72
	ds_read_b32 v73, v73
	ds_read_b32 v74, v74
	ds_read_b32 v75, v75
	ds_read_b32 v76, v76
	ds_read_b32 v77, v77
	ds_read_b32 v78, v78
	ds_read_b32 v79, v79
	s_waitcnt lgkmcnt(0)
	v_mfma_f32_32x32x16_bf16 v[64:79], v[172:175], v[140:143], v[64:79]
	v_max_i32_e32 v80, 0xffffffe0, v88
	v_max_i32_e32 v81, 0xffffffdf, v88
	v_max_i32_e32 v82, 0xffffffde, v88
	v_max_i32_e32 v83, 0xffffffdd, v88
	v_max_i32_e32 v84, 0xffffffd8, v88
	v_max_i32_e32 v85, 0xffffffd7, v88
	v_max_i32_e32 v86, 0xffffffd6, v88
	v_mfma_f32_32x32x16_bf16 v[64:79], v[168:171], v[136:139], v[64:79]
	v_max_i32_e32 v87, 0xffffffd5, v88
	v_max_i32_e32 v89, 0xffffffd0, v88
	v_max_i32_e32 v90, 0xffffffcf, v88
	v_max_i32_e32 v91, 0xffffffce, v88
	v_max_i32_e32 v92, 0xffffffcd, v88
	v_max_i32_e32 v93, 0xffffffc8, v88
	v_max_i32_e32 v94, 0xffffffc7, v88
	v_mfma_f32_32x32x16_bf16 v[64:79], v[164:167], v[132:135], v[64:79]
	v_max_i32_e32 v95, 0xffffffc6, v88
	v_add_u32_e32 v80, 32, v80
	v_add_u32_e32 v81, 33, v81
	v_add_u32_e32 v82, 34, v82
	v_add_u32_e32 v83, 35, v83
	v_add_u32_e32 v84, 40, v84
	v_add_u32_e32 v85, 41, v85
	v_add_u32_e32 v86, 42, v86
	v_add_u32_e32 v87, 43, v87
	v_add_u32_e32 v89, 48, v89
	v_add_u32_e32 v90, 49, v90
	v_add_u32_e32 v91, 50, v91
	v_add_u32_e32 v92, 51, v92
	v_add_u32_e32 v93, 56, v93
	v_add_u32_e32 v94, 57, v94
	v_add_u32_e32 v95, 58, v95
	v_max_i32_e32 v88, 0xffffffc5, v88
	v_min_u32_e32 v80, 0x100, v80
	v_min_u32_e32 v81, 0x100, v81
	v_min_u32_e32 v82, 0x100, v82
	v_min_u32_e32 v83, 0x100, v83
	v_min_u32_e32 v84, 0x100, v84
	v_min_u32_e32 v85, 0x100, v85
	v_min_u32_e32 v86, 0x100, v86
	v_min_u32_e32 v87, 0x100, v87
	v_min_u32_e32 v89, 0x100, v89
	v_min_u32_e32 v90, 0x100, v90
	v_min_u32_e32 v91, 0x100, v91
	v_min_u32_e32 v92, 0x100, v92
	v_min_u32_e32 v93, 0x100, v93
	v_min_u32_e32 v94, 0x100, v94
	v_min_u32_e32 v95, 0x100, v95
	v_add_u32_e32 v88, 59, v88
	v_lshl_add_u32 v80, v80, 2, s62
	v_lshl_add_u32 v81, v81, 2, s62
	v_lshl_add_u32 v82, v82, 2, s62
	v_lshl_add_u32 v83, v83, 2, s62
	v_lshl_add_u32 v84, v84, 2, s62
	v_lshl_add_u32 v85, v85, 2, s62
	v_lshl_add_u32 v86, v86, 2, s62
	v_lshl_add_u32 v87, v87, 2, s62
	v_lshl_add_u32 v89, v89, 2, s62
	v_lshl_add_u32 v90, v90, 2, s62
	v_lshl_add_u32 v91, v91, 2, s62
	v_lshl_add_u32 v92, v92, 2, s62
	v_lshl_add_u32 v93, v93, 2, s62
	v_lshl_add_u32 v94, v94, 2, s62
	v_lshl_add_u32 v95, v95, 2, s62
	v_min_u32_e32 v88, 0x100, v88
	v_mfma_f32_32x32x16_bf16 v[64:79], v[160:163], v[128:131], v[64:79]
	ds_read_b32 v80, v80
	ds_read_b32 v81, v81
	ds_read_b32 v82, v82
	ds_read_b32 v83, v83
	ds_read_b32 v84, v84
	ds_read_b32 v85, v85
	ds_read_b32 v86, v86
	ds_read_b32 v87, v87
	v_lshl_add_u32 v160, v88, 2, s62
	ds_read_b32 v88, v89
	ds_read_b32 v89, v90
	ds_read_b32 v90, v91
	ds_read_b32 v91, v92
	ds_read_b32 v92, v93
	ds_read_b32 v93, v94
	ds_read_b32 v94, v95
	ds_read_b32 v95, v160
	v_mov_b32_e32 v250, 0
	s_waitcnt lgkmcnt(0)
	v_mfma_f32_32x32x16_bf16 v[80:95], v[156:159], v[140:143], v[80:95]
	v_mfma_f32_32x32x16_bf16 v[80:95], v[152:155], v[136:139], v[80:95]
	v_mfma_f32_32x32x16_bf16 v[80:95], v[148:151], v[132:135], v[80:95]
	v_mfma_f32_32x32x16_bf16 v[80:95], v[144:147], v[128:131], v[80:95]

.LBB0_612:
	s_andn2_b64 vcc, exec, s[0:1]
	s_cbranch_vccnz .LBB0_558
	s_mov_b64 s[58:59], s[94:95]
	s_mov_b64 s[42:43], s[94:95]
	s_mov_b64 s[46:47], s[94:95]
	s_mov_b64 s[34:35], s[94:95]
	s_mov_b64 s[0:1], s[94:95]
	s_add_u32 s0, s0, s76
	s_addc_u32 s1, s1, 0
	s_add_u32 s0, s0, 0x20000
	s_addc_u32 s1, s1, 0
	s_ashr_i32 s22, s77, 7
	s_add_i32 s36, s22, 8
	s_lshl_b32 s40, s36, 11
	s_lshl_b32 s36, s36, 12
	s_bfe_u32 s3, s77, 0x20005
	s_add_i32 s41, s36, 0xffffc000
	s_cmp_lt_i32 s22, 0
	s_cselect_b64 s[68:69], -1, 0
	s_and_b64 s[36:37], s[68:69], exec
	s_cselect_b32 s40, s40, s41
	s_lshl_b32 s22, s77, 7
	s_and_b32 s78, s22, 0xf80
	s_add_i32 s36, s40, s78
	s_ashr_i32 s37, s36, 31
	s_lshl_b64 s[60:61], s[36:37], 10
	s_add_u32 s22, s58, s60
	v_mov_b32_e32 v18, v226
	s_addc_u32 s37, s59, s61
	s_lshl_b32 s41, s3, 8
	s_add_u32 s58, s22, s41
	v_lshlrev_b32_e32 v0, 4, v18
	v_add_u32_e32 v30, 0x200, v18
	v_add_u32_e32 v10, 0x400, v18
	v_add_u32_e32 v12, 0x600, v18
	s_addc_u32 s59, s37, 0
	v_and_b32_e32 v20, 0xf0, v0
	v_mov_b32_e32 v21, v177
	v_ashrrev_i32_e32 v22, 4, v18
	v_ashrrev_i32_e32 v24, 4, v30
	v_ashrrev_i32_e32 v26, 4, v10
	v_ashrrev_i32_e32 v28, 4, v12
	s_mul_i32 s22, s3, 0x208
	v_lshl_add_u64 v[0:1], s[58:59], 0, v[20:21]
	s_mov_b64 s[14:15], 0x8b00000
	v_ashrrev_i32_e32 v23, 31, v22
	v_ashrrev_i32_e32 v25, 31, v24
	v_ashrrev_i32_e32 v27, 31, v26
	v_ashrrev_i32_e32 v29, 31, v28
	v_add_u32_e32 v32, s22, v18
	v_lshl_add_u64 v[8:9], v[0:1], 0, s[14:15]
	v_lshlrev_b64 v[16:17], 10, v[22:23]
	v_lshlrev_b64 v[2:3], 10, v[24:25]
	v_lshlrev_b64 v[10:11], 10, v[26:27]
	v_lshlrev_b64 v[12:13], 10, v[28:29]
	v_ashrrev_i32_e32 v33, 31, v32
	v_lshl_add_u64 v[0:1], v[8:9], 0, v[16:17]
	v_lshl_add_u64 v[2:3], v[8:9], 0, v[2:3]
	v_lshl_add_u64 v[10:11], v[8:9], 0, v[10:11]
	v_lshl_add_u64 v[8:9], v[8:9], 0, v[12:13]
	v_lshl_add_u64 v[32:33], v[32:33], 2, s[0:1]
	global_load_dwordx4 v[4:7], v[0:1], off
	s_nop 0
	global_load_dwordx4 v[0:3], v[2:3], off
	s_nop 0
	global_load_dwordx4 v[12:15], v[10:11], off
	s_nop 0
	global_load_dwordx4 v[8:11], v[8:9], off
	v_readfirstlane_b32 s58, v18
	flat_load_dword v21, v[32:33]
	v_mov_b32_e32 v80, 0x100
	v_cmp_lt_u32_e32 vcc, 0x1c0, v18
	s_nop 1
	v_cndmask_b32_e64 v81, 0, 1, vcc
	v_mul_u32_u24_e32 v84, 0x1c1, v81
	v_sub_u32_e32 v82, v18, v84
	v_add_u32_e32 v82, 0xffffffa0, v82
	v_med3_i32 v82, v82, 0, v80
	v_mul_u32_u24_e32 v84, 0x104, v81
	v_add3_u32 v82, v82, v84, s22
	v_mov_b32_e32 v83, 0
	v_lshl_add_u64 v[82:83], v[82:83], 2, s[0:1]
	global_load_dword v88, v[82:83], off
	v_add_u32_e32 v85, 0x200, v18
	v_min_u32_e32 v85, 0x381, v85
	v_add_u32_e32 v86, 0xfffffddf, v85
	v_med3_i32 v86, v86, 0, v80
	v_add_u32_e32 v86, 0x104, v86
	v_add_u32_e32 v86, s22, v86
	v_mov_b32_e32 v87, 0
	v_lshl_add_u64 v[86:87], v[86:87], 2, s[0:1]
	global_load_dword v89, v[86:87], off
	v_cmp_gt_i32_e32 vcc, 8, v18
	v_mov_b32_e32 v19, 0
	v_mov_b32_e32 v25, 0
	s_and_saveexec_b64 s[70:71], vcc
	s_cbranch_execz .LBB0_615
	v_add_u32_e32 v30, s22, v30
	v_ashrrev_i32_e32 v31, 31, v30
	v_lshl_add_u64 v[30:31], v[30:31], 2, s[0:1]
	flat_load_dword v25, v[30:31]

.LBB0_617:
	s_or_b64 exec, exec, s[70:71]
	s_ashr_i32 s41, s40, 31
	s_lshl_b64 s[70:71], s[40:41], 10
	s_add_u32 s37, s42, s70
	s_addc_u32 s48, s43, s71
	s_lshl_b32 s3, s22, 1
	s_add_u32 s37, s37, s3
	s_addc_u32 s48, s48, 0
	s_add_u32 s60, s37, 0xab00000
	s_addc_u32 s61, s48, 0
	v_and_b32_e32 v27, 15, v18
	v_lshlrev_b64 v[32:33], 10, v[22:23]
	s_lshl_b32 s52, s22, 16
	v_lshlrev_b32_e32 v176, 4, v27
	v_lshl_add_u64 v[32:33], s[60:61], 0, v[32:33]
	s_add_u32 s37, s46, s52
	v_lshl_add_u64 v[36:37], v[32:33], 0, v[176:177]
	s_mov_b32 s7, 0x8000
	s_addc_u32 s48, s47, 0
	s_lshl_b64 s[72:73], s[40:41], 1
	v_ashrrev_i32_e32 v34, 3, v18
	v_lshl_add_u64 v[30:31], s[60:61], 0, v[16:17]
	v_add_co_u32_e64 v32, s[40:41], s7, v36
	s_add_u32 s62, s37, s72
	v_lshl_add_u64 v[30:31], v[30:31], 0, v[176:177]
	v_addc_co_u32_e64 v33, s[40:41], 0, v37, s[40:41]
	v_ashrrev_i32_e32 v35, 31, v34
	s_addc_u32 s63, s48, s73
	v_and_b32_e32 v29, 7, v18
	s_waitcnt vmcnt(0)
	global_load_dwordx4 v[96:99], v[30:31], off
	global_load_dwordx4 v[100:103], v[32:33], off
	v_lshlrev_b64 v[32:33], 16, v[34:35]
	v_lshl_add_u64 v[38:39], s[62:63], 0, v[32:33]
	v_lshlrev_b32_e32 v30, 4, v29
	v_mov_b32_e32 v31, v177
	v_lshl_add_u64 v[38:39], v[38:39], 0, v[30:31]
	s_mov_b32 s7, 0xcb00000
	s_mov_b64 s[14:15], 0xcb00000
	v_add_co_u32_e64 v42, s[40:41], s7, v38
	v_lshl_add_u64 v[40:41], v[38:39], 0, s[14:15]
	s_nop 0
	v_addc_co_u32_e64 v43, s[40:41], 0, v39, s[40:41]
	s_mov_b64 s[14:15], 0xcf00000
	s_mov_b32 s7, 0xcf00000
	v_lshl_add_u64 v[44:45], v[38:39], 0, s[14:15]
	v_add_co_u32_e64 v38, s[40:41], s7, v38
	v_readlane_b32 s7, v255, 23
	s_nop 0
	v_addc_co_u32_e64 v39, s[40:41], 0, v39, s[40:41]
	v_add_co_u32_e64 v46, s[40:41], s9, v36
	s_nop 1
	v_addc_co_u32_e64 v47, s[40:41], 0, v37, s[40:41]
	v_add_co_u32_e64 v36, s[40:41], s10, v36
	s_nop 1
	v_addc_co_u32_e64 v37, s[40:41], 0, v37, s[40:41]
	global_load_dwordx4 v[104:107], v[46:47], off
	global_load_dwordx4 v[108:111], v[36:37], off
	global_load_dwordx4 v[120:123], v[42:43], off
	global_load_dwordx4 v[112:115], v[40:41], off offset:128
	global_load_dwordx4 v[124:127], v[38:39], off
	global_load_dwordx4 v[116:119], v[44:45], off offset:128
	v_add_u32_e32 v36, s7, v20
	v_mul_lo_u32 v20, v22, s12
	v_add_u32_e32 v22, v36, v20
	s_waitcnt lgkmcnt(0)
	v_lshlrev_b32_e32 v84, 2, v18
	v_add_u32_e32 v84, 0x1ac00, v84
	ds_write_b32 v84, v88
	v_lshlrev_b32_e32 v85, 2, v85
	v_add_u32_e32 v85, 0x1ac00, v85
	ds_write_b32 v85, v89
	ds_write_b128 v22, v[4:7]
	v_mad_u64_u32 v[4:5], s[40:41], v24, s12, v[36:37]
	ds_write_b128 v4, v[0:3]
	v_mad_u64_u32 v[0:1], s[40:41], v26, s12, v[36:37]
	ds_write_b128 v0, v[12:15]
	v_mad_u64_u32 v[0:1], s[40:41], v28, s12, v[36:37]
	ds_write_b128 v0, v[8:11]
	v_lshl_add_u32 v0, v18, 2, 0
	v_add_u32_e32 v1, 0x11800, v0
	ds_write_b32 v1, v21
	s_and_saveexec_b64 s[40:41], vcc
	ds_write_b32 v1, v25 offset:2048
	s_or_b64 exec, exec, s[40:41]
	s_and_saveexec_b64 s[40:41], s[0:1]
	v_add_u32_e32 v0, 0x1a900, v0
	ds_write_b32 v0, v19
	s_or_b64 exec, exec, s[40:41]
	s_ashr_i32 s60, s58, 8
	s_lshl_b32 s40, s60, 7
	s_bfe_u32 s61, s58, 0x20006
	s_add_i32 s0, s40, 0
	s_lshr_b32 s59, s58, 6
	v_and_b32_e32 v2, 31, v18
	s_lshl_b32 s37, s61, 5
	s_add_i32 s0, s0, 0x12100
	v_or_b32_e32 v1, s37, v2
	v_mov_b32_e32 v3, s0
	s_and_b64 s[0:1], s[68:69], exec
	v_lshlrev_b32_e32 v0, 3, v18
	v_mad_u32_u24 v3, v1, s12, v3
	v_add_u32_e32 v1, 0, v20
	s_movk_i32 s0, 0x90
	v_and_b32_e32 v0, 8, v0
	v_add_u32_e32 v239, v1, v176
	v_mul_lo_u32 v1, v34, s0
	v_and_or_b32 v0, v30, s8, v0
	v_add_u32_e32 v1, 0, v1
	s_mul_i32 s0, s60, 0x410
	v_bfe_u32 v236, v18, 5, 1
	s_cselect_b32 s62, 32, 64
	v_add_u32_e32 v240, v1, v0
	s_add_i32 s63, s0, 0
	s_or_b32 s69, s37, s78
	v_mad_u32_u24 v0, v2, s12, 0
	v_lshlrev_b32_e32 v1, 7, v2
	v_lshlrev_b32_e32 v237, 4, v236
	s_add_i32 s63, s63, 0x11800
	v_add_u32_e32 v4, s40, v0
	v_sub_u32_e32 v0, v0, v1
	s_add_i32 s68, s69, 0x9f
	s_addk_i32 s69, 0x5f
	v_add_u32_e32 v243, v0, v237
	v_lshl_add_u64 v[0:1], s[52:53], 0, v[32:33]
	v_mov_b32_e32 v31, v177
	s_add_u32 s0, s46, s72
	v_lshl_add_u64 v[0:1], v[0:1], 0, v[30:31]
	s_addc_u32 s1, s47, s73
	v_lshl_add_u64 v[0:1], s[0:1], 0, v[0:1]
	s_mov_b64 s[0:1], 0xcf00180
	v_lshl_add_u64 v[190:191], v[0:1], 0, s[0:1]
	s_lshl_b32 s0, s77, 3
	s_and_b32 s0, s0, 0x300
	s_add_u32 s0, s0, s70
	s_addc_u32 s1, 0, s71
	v_lshl_add_u64 v[0:1], s[0:1], 0, v[16:17]
	v_lshl_add_u64 v[0:1], v[0:1], 0, v[176:177]
	v_lshlrev_b32_e32 v235, 2, v236
	v_lshl_add_u64 v[0:1], s[42:43], 0, v[0:1]
	s_mov_b64 s[0:1], 0xab38000
	v_lshl_add_u64 v[192:193], v[0:1], 0, s[0:1]
	v_sub_u32_e32 v0, v235, v2
	v_subrev_u32_e32 v0, s37, v0
	s_add_i32 s0, s37, s78
	v_mov_b32_e32 v248, 0
	v_lshlrev_b32_e32 v233, 3, v27
	v_and_b32_e32 v234, 63, v18
	v_add_u32_e32 v241, 0x8800, v240
	v_add_u32_e32 v242, 0xa800, v240
	v_mul_u32_u24_e32 v238, 0x110, v2
	v_add_u32_e32 v244, 0xd000, v243
	s_mov_b32 s22, 3
	v_subrev_u32_e32 v245, s78, v0
	s_mov_b32 s42, 0
	s_sub_i32 s43, 0, s0
	v_add_u32_e32 v246, v4, v237
	v_add_u32_e32 v247, v3, v237
	v_mov_b32_e32 v0, 0
	v_mov_b32_e32 v1, v248
	v_mov_b32_e32 v2, v248
	v_mov_b32_e32 v3, v248
	v_mov_b32_e32 v4, v248
	v_mov_b32_e32 v5, v248
	v_mov_b32_e32 v6, v248
	v_mov_b32_e32 v7, v248
	v_mov_b32_e32 v8, v248
	v_mov_b32_e32 v9, v248
	v_mov_b32_e32 v10, v248
	v_mov_b32_e32 v11, v248
	v_mov_b32_e32 v12, v248
	v_mov_b32_e32 v13, v248
	v_mov_b32_e32 v14, v248
	v_mov_b32_e32 v15, v248
	v_mov_b32_e32 v16, 0
	v_mov_b32_e32 v17, v248
	v_mov_b32_e32 v18, v248
	v_mov_b32_e32 v19, v248
	v_mov_b32_e32 v20, v248
	v_mov_b32_e32 v21, v248
	v_mov_b32_e32 v22, v248
	v_mov_b32_e32 v23, v248
	v_mov_b32_e32 v24, v248
	v_mov_b32_e32 v25, v248
	v_mov_b32_e32 v26, v248
	v_mov_b32_e32 v27, v248
	v_mov_b32_e32 v28, v248
	v_mov_b32_e32 v29, v248
	v_mov_b32_e32 v30, v248
	v_mov_b32_e32 v31, v248
	v_mov_b32_e32 v32, 0
	v_mov_b32_e32 v33, v248
	v_mov_b32_e32 v34, v248
	v_mov_b32_e32 v35, v248
	v_mov_b32_e32 v36, v248
	v_mov_b32_e32 v37, v248
	v_mov_b32_e32 v38, v248
	v_mov_b32_e32 v39, v248
	v_mov_b32_e32 v40, v248
	v_mov_b32_e32 v41, v248
	v_mov_b32_e32 v42, v248
	v_mov_b32_e32 v43, v248
	v_mov_b32_e32 v44, v248
	v_mov_b32_e32 v45, v248
	v_mov_b32_e32 v46, v248
	v_mov_b32_e32 v47, v248
	v_mov_b32_e32 v48, 0
	v_mov_b32_e32 v49, v248
	v_mov_b32_e32 v50, v248
	v_mov_b32_e32 v51, v248
	v_mov_b32_e32 v52, v248
	v_mov_b32_e32 v53, v248
	v_mov_b32_e32 v54, v248
	v_mov_b32_e32 v55, v248
	v_mov_b32_e32 v56, v248
	v_mov_b32_e32 v57, v248
	v_mov_b32_e32 v58, v248
	v_mov_b32_e32 v59, v248
	v_mov_b32_e32 v60, v248
	v_mov_b32_e32 v61, v248
	v_mov_b32_e32 v62, v248
	v_mov_b32_e32 v63, v248
	s_waitcnt vmcnt(0)
	ds_write_b128 v239, v[96:99]
	ds_write_b128 v239, v[100:103] offset:8704
	ds_write2_b64 v241, v[120:121], v[122:123] offset1:2
	ds_write2_b64 v242, v[124:125], v[126:127] offset0:128 offset1:130
	s_waitcnt lgkmcnt(0)
	s_barrier
	ds_read_b128 v[222:225], v247
	ds_read_b128 v[218:221], v247 offset:32
	ds_read_b128 v[214:217], v247 offset:64
	ds_read_b128 v[210:213], v247 offset:96
	s_mov_b32 s100, -1
	s_branch .LBB0_623

.La2t0_near:
	v_add_u32_e32 v249, s42, v245
	s_mul_i32 s101, s60, 0x704
	s_add_i32 s101, s101, 0x1af80
	v_lshl_add_u32 v251, v249, 2, s101
	ds_read_b32 v64, v251 offset:0
	ds_read_b32 v65, v251 offset:4
	ds_read_b32 v66, v251 offset:8
	ds_read_b32 v67, v251 offset:12
	ds_read_b32 v68, v251 offset:32
	ds_read_b32 v69, v251 offset:36
	ds_read_b32 v70, v251 offset:40
	ds_read_b32 v71, v251 offset:44
	ds_read_b32 v72, v251 offset:64
	ds_read_b32 v73, v251 offset:68
	ds_read_b32 v74, v251 offset:72
	ds_read_b32 v75, v251 offset:76
	ds_read_b32 v76, v251 offset:96
	ds_read_b32 v77, v251 offset:100
	ds_read_b32 v78, v251 offset:104
	ds_read_b32 v79, v251 offset:108
	ds_read_b32 v80, v251 offset:128
	ds_read_b32 v81, v251 offset:132
	ds_read_b32 v82, v251 offset:136
	ds_read_b32 v83, v251 offset:140
	ds_read_b32 v84, v251 offset:160
	ds_read_b32 v85, v251 offset:164
	ds_read_b32 v86, v251 offset:168
	ds_read_b32 v87, v251 offset:172
	ds_read_b32 v88, v251 offset:192
	ds_read_b32 v89, v251 offset:196
	ds_read_b32 v90, v251 offset:200
	ds_read_b32 v91, v251 offset:204
	ds_read_b32 v92, v251 offset:224
	ds_read_b32 v93, v251 offset:228
	ds_read_b32 v94, v251 offset:232
	ds_read_b32 v95, v251 offset:236
	s_waitcnt lgkmcnt(0)
	ds_read_b128 v[128:131], v243 offset:44032
	ds_read_b128 v[132:135], v243 offset:44064
	ds_read_b128 v[136:139], v243 offset:48640
	ds_read_b128 v[140:143], v243 offset:48672
	s_cmp_eq_u64 s[0:1], 0
	v_mfma_f32_32x32x16_bf16 v[64:79], v[172:175], v[222:225], v[64:79]
	s_cbranch_scc1 .La2t0n_nl0
	v_add_co_u32_e32 v186, vcc, 0xfffe8000, v192
	s_nop 1
	v_addc_co_u32_e32 v187, vcc, -1, v193, vcc
	global_load_dwordx4 v[96:99], v[186:187], off
.La2t0n_nl0:
	v_mfma_f32_32x32x16_bf16 v[64:79], v[168:171], v[218:221], v[64:79]
	s_cbranch_scc1 .La2t0n_nl1
	v_add_co_u32_e32 v186, vcc, 0xffff0000, v192
	s_nop 1
	v_addc_co_u32_e32 v187, vcc, -1, v193, vcc
	global_load_dwordx4 v[100:103], v[186:187], off
.La2t0n_nl1:
	v_mfma_f32_32x32x16_bf16 v[64:79], v[164:167], v[214:217], v[64:79]
	s_cbranch_scc1 .La2t0n_nl2
	v_add_co_u32_e32 v186, vcc, 0xffbfff80, v190
	s_nop 1
	v_addc_co_u32_e32 v187, vcc, -1, v191, vcc
	global_load_dwordx4 v[120:123], v[186:187], off
.La2t0n_nl2:
	v_mfma_f32_32x32x16_bf16 v[64:79], v[160:163], v[210:213], v[64:79]
	s_cbranch_scc1 .La2t0n_nl3
	v_add_co_u32_e32 v186, vcc, 0xffffff80, v190
	s_nop 1
	v_addc_co_u32_e32 v187, vcc, -1, v191, vcc
	global_load_dwordx4 v[124:127], v[186:187], off
.La2t0n_nl3:
	v_mfma_f32_32x32x16_bf16 v[80:95], v[156:159], v[222:225], v[80:95]
	s_nop 11
	v_exp_f32_e32 v64, v64
	v_exp_f32_e32 v65, v65
	v_exp_f32_e32 v66, v66
	v_exp_f32_e32 v67, v67
	v_exp_f32_e32 v68, v68
	v_exp_f32_e32 v69, v69
	v_mfma_f32_32x32x16_bf16 v[80:95], v[152:155], v[218:221], v[80:95]
	v_exp_f32_e32 v70, v70
	v_exp_f32_e32 v71, v71
	v_exp_f32_e32 v72, v72
	v_exp_f32_e32 v73, v73
	v_exp_f32_e32 v74, v74
	v_exp_f32_e32 v75, v75
	v_mfma_f32_32x32x16_bf16 v[80:95], v[148:151], v[214:217], v[80:95]
	v_exp_f32_e32 v76, v76
	v_exp_f32_e32 v77, v77
	v_exp_f32_e32 v78, v78
	v_exp_f32_e32 v79, v79
	v_cvt_pk_bf16_f32 v160, v64, v65
	v_cvt_pk_bf16_f32 v161, v66, v67
	v_mfma_f32_32x32x16_bf16 v[80:95], v[144:147], v[210:213], v[80:95]
	ds_read_b128 v[144:147], v243 offset:34816
	ds_read_b128 v[148:151], v243 offset:34848
	ds_read_b128 v[152:155], v243 offset:39424
	ds_read_b128 v[156:159], v243 offset:39456
	v_cvt_pk_bf16_f32 v162, v68, v69
	v_cvt_pk_bf16_f32 v163, v70, v71
	v_cvt_pk_bf16_f32 v164, v72, v73
	v_cvt_pk_bf16_f32 v165, v74, v75
	v_cvt_pk_bf16_f32 v166, v76, v77
	v_cvt_pk_bf16_f32 v167, v78, v79
	s_nop 4
	v_exp_f32_e32 v80, v80
	v_exp_f32_e32 v81, v81
	v_exp_f32_e32 v82, v82
	v_exp_f32_e32 v83, v83
	s_waitcnt lgkmcnt(7)
	v_mfma_f32_32x32x16_bf16 v[16:31], v[128:131], v[160:163], v[16:31]
	s_cmp_eq_u64 s[0:1], 0
	s_cbranch_scc1 .La2t0n_lv_a
	s_waitcnt vmcnt(4)
	s_branch .La2t0n_lv_b

.La2t0n_lv_b:
	v_add_u32_e32 v251, 0xd000, v240
	ds_write_b128 v239, v[104:107] offset:17408
	ds_write_b128 v239, v[108:111] offset:26112
	ds_write2_b64 v251, v[112:113], v[114:115] offset1:2
	v_add_u32_e32 v251, 0xf000, v240
	ds_write2_b64 v251, v[116:117], v[118:119] offset0:128 offset1:130
	v_exp_f32_e32 v84, v84
	v_exp_f32_e32 v85, v85
	v_exp_f32_e32 v86, v86
	s_waitcnt lgkmcnt(6)
	v_mfma_f32_32x32x16_bf16 v[16:31], v[132:135], v[164:167], v[16:31]
	ds_read_b128 v[128:131], v243 offset:44096
	ds_read_b128 v[132:135], v243 offset:44128
	v_exp_f32_e32 v87, v87
	v_exp_f32_e32 v88, v88
	v_exp_f32_e32 v89, v89
	s_waitcnt lgkmcnt(7)
	v_mfma_f32_32x32x16_bf16 v[0:15], v[136:139], v[160:163], v[0:15]
	v_exp_f32_e32 v90, v90
	v_exp_f32_e32 v91, v91
	v_exp_f32_e32 v92, v92
	s_waitcnt lgkmcnt(6)
	v_mfma_f32_32x32x16_bf16 v[0:15], v[140:143], v[164:167], v[0:15]
	ds_read_b128 v[136:139], v243 offset:48704
	ds_read_b128 v[140:143], v243 offset:48736
	v_exp_f32_e32 v93, v93
	v_exp_f32_e32 v94, v94
	v_exp_f32_e32 v95, v95
	s_waitcnt lgkmcnt(7)
	v_mfma_f32_32x32x16_bf16 v[48:63], v[144:147], v[160:163], v[48:63]
	v_cvt_pk_bf16_f32 v168, v80, v81
	v_cvt_pk_bf16_f32 v169, v82, v83
	s_waitcnt lgkmcnt(6)
	v_mfma_f32_32x32x16_bf16 v[48:63], v[148:151], v[164:167], v[48:63]
	ds_read_b128 v[144:147], v243 offset:34880
	ds_read_b128 v[148:151], v243 offset:34912
	v_cvt_pk_bf16_f32 v170, v84, v85
	v_cvt_pk_bf16_f32 v171, v86, v87
	s_waitcnt lgkmcnt(7)
	v_mfma_f32_32x32x16_bf16 v[32:47], v[152:155], v[160:163], v[32:47]
	v_cvt_pk_bf16_f32 v172, v88, v89
	v_cvt_pk_bf16_f32 v173, v90, v91
	s_waitcnt lgkmcnt(6)
	v_mfma_f32_32x32x16_bf16 v[32:47], v[156:159], v[164:167], v[32:47]
	ds_read_b128 v[152:155], v243 offset:39488
	ds_read_b128 v[156:159], v243 offset:39520
	v_cvt_pk_bf16_f32 v174, v92, v93
	v_cvt_pk_bf16_f32 v175, v94, v95
	s_nop 1
	s_waitcnt lgkmcnt(7)
	v_mfma_f32_32x32x16_bf16 v[16:31], v[128:131], v[168:171], v[16:31]
	v_add_f32_e32 v186, v64, v67
	v_add_f32_e32 v187, v65, v68
	v_add_f32_e32 v251, v66, v69
	v_add_f32_e32 v186, v186, v70
	v_add_f32_e32 v187, v187, v71
	s_waitcnt lgkmcnt(6)
	v_mfma_f32_32x32x16_bf16 v[16:31], v[132:135], v[172:175], v[16:31]
	v_add_f32_e32 v251, v251, v72
	v_add_f32_e32 v186, v186, v73
	v_add_f32_e32 v187, v187, v74
	v_add_f32_e32 v251, v251, v75
	v_add_f32_e32 v186, v186, v76
	s_waitcnt lgkmcnt(5)
	v_mfma_f32_32x32x16_bf16 v[0:15], v[136:139], v[168:171], v[0:15]
	v_add_f32_e32 v187, v187, v77
	v_add_f32_e32 v251, v251, v78
	v_add_f32_e32 v186, v186, v79
	v_add_f32_e32 v187, v187, v80
	v_add_f32_e32 v251, v251, v81
	s_waitcnt lgkmcnt(4)
	v_mfma_f32_32x32x16_bf16 v[0:15], v[140:143], v[172:175], v[0:15]
	v_add_f32_e32 v186, v186, v82
	v_add_f32_e32 v187, v187, v83
	v_add_f32_e32 v251, v251, v84
	v_add_f32_e32 v186, v186, v85
	v_add_f32_e32 v187, v187, v86
	s_waitcnt lgkmcnt(3)
	v_mfma_f32_32x32x16_bf16 v[48:63], v[144:147], v[168:171], v[48:63]
	v_add_f32_e32 v251, v251, v87
	v_add_f32_e32 v186, v186, v88
	v_add_f32_e32 v187, v187, v89
	v_add_f32_e32 v251, v251, v90
	v_add_f32_e32 v186, v186, v91
	s_waitcnt lgkmcnt(2)
	v_mfma_f32_32x32x16_bf16 v[48:63], v[148:151], v[172:175], v[48:63]
	v_add_f32_e32 v187, v187, v92
	v_add_f32_e32 v251, v251, v93
	v_add_f32_e32 v186, v186, v94
	v_add_f32_e32 v187, v187, v95
	v_add_f32_e32 v186, v186, v187
	s_waitcnt lgkmcnt(1)
	v_mfma_f32_32x32x16_bf16 v[32:47], v[152:155], v[168:171], v[32:47]
	v_add_f32_e32 v186, v186, v251
	v_add_f32_e32 v248, v248, v186
	s_waitcnt lgkmcnt(0)
	v_mfma_f32_32x32x16_bf16 v[32:47], v[156:159], v[172:175], v[32:47]
	s_setprio 0
	s_branch .La2t0_pw
.LBB0_627:
	v_add_u32_e32 v249, s42, v245

.La2t1_near:
	s_mul_i32 s101, s60, 0x704
	s_add_i32 s101, s101, 0x1b080
	v_lshl_add_u32 v251, v249, 2, s101
	ds_read_b32 v64, v251 offset:0
	ds_read_b32 v65, v251 offset:4
	ds_read_b32 v66, v251 offset:8
	ds_read_b32 v67, v251 offset:12
	ds_read_b32 v68, v251 offset:32
	ds_read_b32 v69, v251 offset:36
	ds_read_b32 v70, v251 offset:40
	ds_read_b32 v71, v251 offset:44
	ds_read_b32 v72, v251 offset:64
	ds_read_b32 v73, v251 offset:68
	ds_read_b32 v74, v251 offset:72
	ds_read_b32 v75, v251 offset:76
	ds_read_b32 v76, v251 offset:96
	ds_read_b32 v77, v251 offset:100
	ds_read_b32 v78, v251 offset:104
	ds_read_b32 v79, v251 offset:108
	ds_read_b32 v80, v251 offset:128
	ds_read_b32 v81, v251 offset:132
	ds_read_b32 v82, v251 offset:136
	ds_read_b32 v83, v251 offset:140
	ds_read_b32 v84, v251 offset:160
	ds_read_b32 v85, v251 offset:164
	ds_read_b32 v86, v251 offset:168
	ds_read_b32 v87, v251 offset:172
	ds_read_b32 v88, v251 offset:192
	ds_read_b32 v89, v251 offset:196
	ds_read_b32 v90, v251 offset:200
	ds_read_b32 v91, v251 offset:204
	ds_read_b32 v92, v251 offset:224
	ds_read_b32 v93, v251 offset:228
	ds_read_b32 v94, v251 offset:232
	ds_read_b32 v95, v251 offset:236
	s_waitcnt lgkmcnt(0)
	ds_read_b128 v[128:131], v243 offset:62464
	ds_read_b128 v[132:135], v243 offset:62496
	ds_read_b128 v[136:139], v244 offset:13824
	ds_read_b128 v[140:143], v244 offset:13856
	s_cmp_eq_u64 s[0:1], 0
	v_mfma_f32_32x32x16_bf16 v[64:79], v[172:175], v[222:225], v[64:79]
	s_cbranch_scc1 .La2t1n_nl0
	v_add_co_u32_e32 v186, vcc, 0xffff8000, v192
	s_nop 1
	v_addc_co_u32_e32 v187, vcc, -1, v193, vcc
	global_load_dwordx4 v[104:107], v[186:187], off
.La2t1n_nl0:
	v_mfma_f32_32x32x16_bf16 v[64:79], v[168:171], v[218:221], v[64:79]
	s_cbranch_scc1 .La2t1n_nl1
	global_load_dwordx4 v[108:111], v[192:193], off
.La2t1n_nl1:
	v_mfma_f32_32x32x16_bf16 v[64:79], v[164:167], v[214:217], v[64:79]
	s_cbranch_scc1 .La2t1n_nl2
	v_add_co_u32_e32 v186, vcc, 0xffc00000, v190
	s_nop 1
	v_addc_co_u32_e32 v187, vcc, -1, v191, vcc
	global_load_dwordx4 v[112:115], v[186:187], off
.La2t1n_nl2:
	v_mfma_f32_32x32x16_bf16 v[64:79], v[160:163], v[210:213], v[64:79]
	s_cbranch_scc1 .La2t1n_nl3
	global_load_dwordx4 v[116:119], v[190:191], off
.La2t1n_nl3:
	v_mfma_f32_32x32x16_bf16 v[80:95], v[156:159], v[222:225], v[80:95]
	s_nop 11
	v_exp_f32_e32 v64, v64
	v_exp_f32_e32 v65, v65
	v_exp_f32_e32 v66, v66
	v_exp_f32_e32 v67, v67
	v_exp_f32_e32 v68, v68
	v_exp_f32_e32 v69, v69
	v_mfma_f32_32x32x16_bf16 v[80:95], v[152:155], v[218:221], v[80:95]
	v_exp_f32_e32 v70, v70
	v_exp_f32_e32 v71, v71
	v_exp_f32_e32 v72, v72
	v_exp_f32_e32 v73, v73
	v_exp_f32_e32 v74, v74
	v_exp_f32_e32 v75, v75
	v_mfma_f32_32x32x16_bf16 v[80:95], v[148:151], v[214:217], v[80:95]
	v_exp_f32_e32 v76, v76
	v_exp_f32_e32 v77, v77
	v_exp_f32_e32 v78, v78
	v_exp_f32_e32 v79, v79
	v_cvt_pk_bf16_f32 v160, v64, v65
	v_cvt_pk_bf16_f32 v161, v66, v67
	v_mfma_f32_32x32x16_bf16 v[80:95], v[144:147], v[210:213], v[80:95]
	ds_read_b128 v[144:147], v243 offset:53248
	ds_read_b128 v[148:151], v243 offset:53280
	ds_read_b128 v[152:155], v243 offset:57856
	ds_read_b128 v[156:159], v243 offset:57888
	v_cvt_pk_bf16_f32 v162, v68, v69
	v_cvt_pk_bf16_f32 v163, v70, v71
	v_cvt_pk_bf16_f32 v164, v72, v73
	v_cvt_pk_bf16_f32 v165, v74, v75
	v_cvt_pk_bf16_f32 v166, v76, v77
	v_cvt_pk_bf16_f32 v167, v78, v79
	s_nop 4
	v_exp_f32_e32 v80, v80
	v_exp_f32_e32 v81, v81
	v_exp_f32_e32 v82, v82
	v_exp_f32_e32 v83, v83
	s_waitcnt lgkmcnt(7)
	v_mfma_f32_32x32x16_bf16 v[16:31], v[128:131], v[160:163], v[16:31]
	s_cmp_eq_u64 s[0:1], 0
	s_cbranch_scc1 .La2t1n_lv_s
	s_waitcnt vmcnt(4)
	ds_write_b128 v239, v[96:99]
	ds_write_b128 v239, v[100:103] offset:8704
	ds_write2_b64 v241, v[120:121], v[122:123] offset1:2
	ds_write2_b64 v242, v[124:125], v[126:127] offset0:128 offset1:130
.La2t1n_lv_s:
	v_exp_f32_e32 v84, v84
	v_exp_f32_e32 v85, v85
	v_exp_f32_e32 v86, v86
	s_waitcnt lgkmcnt(6)
	v_mfma_f32_32x32x16_bf16 v[16:31], v[132:135], v[164:167], v[16:31]
	ds_read_b128 v[128:131], v243 offset:62528
	ds_read_b128 v[132:135], v243 offset:62560
	v_exp_f32_e32 v87, v87
	v_exp_f32_e32 v88, v88
	v_exp_f32_e32 v89, v89
	s_waitcnt lgkmcnt(7)
	v_mfma_f32_32x32x16_bf16 v[0:15], v[136:139], v[160:163], v[0:15]
	v_exp_f32_e32 v90, v90
	v_exp_f32_e32 v91, v91
	v_exp_f32_e32 v92, v92
	s_waitcnt lgkmcnt(6)
	v_mfma_f32_32x32x16_bf16 v[0:15], v[140:143], v[164:167], v[0:15]
	ds_read_b128 v[136:139], v244 offset:13888
	ds_read_b128 v[140:143], v244 offset:13920
	v_exp_f32_e32 v93, v93
	v_exp_f32_e32 v94, v94
	v_exp_f32_e32 v95, v95
	s_waitcnt lgkmcnt(7)
	v_mfma_f32_32x32x16_bf16 v[48:63], v[144:147], v[160:163], v[48:63]
	v_cvt_pk_bf16_f32 v168, v80, v81
	v_cvt_pk_bf16_f32 v169, v82, v83
	s_waitcnt lgkmcnt(6)
	v_mfma_f32_32x32x16_bf16 v[48:63], v[148:151], v[164:167], v[48:63]
	ds_read_b128 v[144:147], v243 offset:53312
	ds_read_b128 v[148:151], v243 offset:53344
	v_cvt_pk_bf16_f32 v170, v84, v85
	v_cvt_pk_bf16_f32 v171, v86, v87
	s_waitcnt lgkmcnt(7)
	v_mfma_f32_32x32x16_bf16 v[32:47], v[152:155], v[160:163], v[32:47]
	v_cvt_pk_bf16_f32 v172, v88, v89
	v_cvt_pk_bf16_f32 v173, v90, v91
	s_waitcnt lgkmcnt(6)
	v_mfma_f32_32x32x16_bf16 v[32:47], v[156:159], v[164:167], v[32:47]
	ds_read_b128 v[152:155], v243 offset:57920
	ds_read_b128 v[156:159], v243 offset:57952
	v_cvt_pk_bf16_f32 v174, v92, v93
	v_cvt_pk_bf16_f32 v175, v94, v95
	s_nop 1
	s_waitcnt lgkmcnt(7)
	v_mfma_f32_32x32x16_bf16 v[16:31], v[128:131], v[168:171], v[16:31]
	v_add_f32_e32 v186, v64, v67
	v_add_f32_e32 v187, v65, v68
	v_add_f32_e32 v251, v66, v69
	v_add_f32_e32 v186, v186, v70
	v_add_f32_e32 v187, v187, v71
	s_waitcnt lgkmcnt(6)
	v_mfma_f32_32x32x16_bf16 v[16:31], v[132:135], v[172:175], v[16:31]
	v_add_f32_e32 v251, v251, v72
	v_add_f32_e32 v186, v186, v73
	v_add_f32_e32 v187, v187, v74
	v_add_f32_e32 v251, v251, v75
	v_add_f32_e32 v186, v186, v76
	s_waitcnt lgkmcnt(5)
	v_mfma_f32_32x32x16_bf16 v[0:15], v[136:139], v[168:171], v[0:15]
	v_add_f32_e32 v187, v187, v77
	v_add_f32_e32 v251, v251, v78
	v_add_f32_e32 v186, v186, v79
	v_add_f32_e32 v187, v187, v80
	v_add_f32_e32 v251, v251, v81
	s_waitcnt lgkmcnt(4)
	v_mfma_f32_32x32x16_bf16 v[0:15], v[140:143], v[172:175], v[0:15]
	v_add_f32_e32 v186, v186, v82
	v_add_f32_e32 v187, v187, v83
	v_add_f32_e32 v251, v251, v84
	v_add_f32_e32 v186, v186, v85
	v_add_f32_e32 v187, v187, v86
	s_waitcnt lgkmcnt(3)
	v_mfma_f32_32x32x16_bf16 v[48:63], v[144:147], v[168:171], v[48:63]
	v_add_f32_e32 v251, v251, v87
	v_add_f32_e32 v186, v186, v88
	v_add_f32_e32 v187, v187, v89
	v_add_f32_e32 v251, v251, v90
	v_add_f32_e32 v186, v186, v91
	s_waitcnt lgkmcnt(2)
	v_mfma_f32_32x32x16_bf16 v[48:63], v[148:151], v[172:175], v[48:63]
	v_add_f32_e32 v187, v187, v92
	v_add_f32_e32 v251, v251, v93
	v_add_f32_e32 v186, v186, v94
	v_add_f32_e32 v187, v187, v95
	v_add_f32_e32 v186, v186, v187
	s_waitcnt lgkmcnt(1)
	v_mfma_f32_32x32x16_bf16 v[32:47], v[152:155], v[168:171], v[32:47]
	v_add_f32_e32 v186, v186, v251
	v_add_f32_e32 v248, v248, v186
	s_waitcnt lgkmcnt(0)
	v_mfma_f32_32x32x16_bf16 v[32:47], v[156:159], v[172:175], v[32:47]
	s_setprio 0
	s_branch .LBB0_622
.LBB0_633:
.LBB0_634:
	s_nop 9
	v_add_u32_e32 v88, 0xc0, v249
	v_max_i32_e32 v65, -1, v88
	v_max_i32_e32 v66, -2, v88
	v_max_i32_e32 v67, -3, v88
	v_max_i32_e32 v68, -8, v88
	v_max_i32_e32 v69, -9, v88
	v_max_i32_e32 v70, -10, v88
	v_max_i32_e32 v71, -11, v88
	v_max_i32_e32 v72, -16, v88
	v_max_i32_e32 v73, 0xffffffef, v88
	v_max_i32_e32 v74, 0xffffffee, v88
	v_max_i32_e32 v75, 0xffffffed, v88
	v_max_i32_e32 v76, 0xffffffe8, v88
	v_max_i32_e32 v77, 0xffffffe7, v88
	v_max_i32_e32 v78, 0xffffffe6, v88
	v_max_i32_e32 v79, 0xffffffe5, v88
	v_add_u32_e32 v65, 1, v65
	v_add_u32_e32 v66, 2, v66
	v_add_u32_e32 v67, 3, v67
	v_add_u32_e32 v68, 8, v68
	v_add_u32_e32 v69, 9, v69
	v_add_u32_e32 v70, 10, v70
	v_add_u32_e32 v71, 11, v71
	v_add_u32_e32 v72, 16, v72
	v_add_u32_e32 v73, 17, v73
	v_add_u32_e32 v74, 18, v74
	v_add_u32_e32 v75, 19, v75
	v_add_u32_e32 v76, 24, v76
	v_add_u32_e32 v77, 25, v77
	v_add_u32_e32 v78, 26, v78
	v_add_u32_e32 v79, 27, v79
	v_med3_i32 v64, v88, 0, v232
	v_min_u32_e32 v65, 0x100, v65
	v_min_u32_e32 v66, 0x100, v66
	v_min_u32_e32 v67, 0x100, v67
	v_min_u32_e32 v68, 0x100, v68
	v_min_u32_e32 v69, 0x100, v69
	v_min_u32_e32 v70, 0x100, v70
	v_min_u32_e32 v71, 0x100, v71
	v_min_u32_e32 v72, 0x100, v72
	v_min_u32_e32 v73, 0x100, v73
	v_min_u32_e32 v74, 0x100, v74
	v_min_u32_e32 v75, 0x100, v75
	v_min_u32_e32 v76, 0x100, v76
	v_min_u32_e32 v77, 0x100, v77
	v_min_u32_e32 v78, 0x100, v78
	v_min_u32_e32 v79, 0x100, v79
	v_lshl_add_u32 v64, v64, 2, s63
	v_lshl_add_u32 v65, v65, 2, s63
	v_lshl_add_u32 v66, v66, 2, s63
	v_lshl_add_u32 v67, v67, 2, s63
	v_lshl_add_u32 v68, v68, 2, s63
	v_lshl_add_u32 v69, v69, 2, s63
	v_lshl_add_u32 v70, v70, 2, s63
	v_lshl_add_u32 v71, v71, 2, s63
	v_lshl_add_u32 v72, v72, 2, s63
	v_lshl_add_u32 v73, v73, 2, s63
	v_lshl_add_u32 v74, v74, 2, s63
	v_lshl_add_u32 v75, v75, 2, s63
	v_lshl_add_u32 v76, v76, 2, s63
	v_lshl_add_u32 v77, v77, 2, s63
	v_lshl_add_u32 v78, v78, 2, s63
	v_lshl_add_u32 v79, v79, 2, s63
	ds_read_b32 v64, v64
	ds_read_b32 v65, v65
	ds_read_b32 v66, v66
	ds_read_b32 v67, v67
	ds_read_b32 v68, v68
	ds_read_b32 v69, v69
	ds_read_b32 v70, v70
	ds_read_b32 v71, v71
	ds_read_b32 v72, v72
	ds_read_b32 v73, v73
	ds_read_b32 v74, v74
	ds_read_b32 v75, v75
	ds_read_b32 v76, v76
	ds_read_b32 v77, v77
	ds_read_b32 v78, v78
	ds_read_b32 v79, v79
	s_waitcnt lgkmcnt(0)
	v_mfma_f32_32x32x16_bf16 v[64:79], v[172:175], v[140:143], v[64:79]
	v_max_i32_e32 v80, 0xffffffe0, v88
	v_max_i32_e32 v81, 0xffffffdf, v88
	v_max_i32_e32 v82, 0xffffffde, v88
	v_max_i32_e32 v83, 0xffffffdd, v88
	v_max_i32_e32 v84, 0xffffffd8, v88
	v_max_i32_e32 v85, 0xffffffd7, v88
	v_max_i32_e32 v86, 0xffffffd6, v88
	v_mfma_f32_32x32x16_bf16 v[64:79], v[168:171], v[136:139], v[64:79]
	v_max_i32_e32 v87, 0xffffffd5, v88
	v_max_i32_e32 v89, 0xffffffd0, v88
	v_max_i32_e32 v90, 0xffffffcf, v88
	v_max_i32_e32 v91, 0xffffffce, v88
	v_max_i32_e32 v92, 0xffffffcd, v88
	v_max_i32_e32 v93, 0xffffffc8, v88
	v_max_i32_e32 v94, 0xffffffc7, v88
	v_mfma_f32_32x32x16_bf16 v[64:79], v[164:167], v[132:135], v[64:79]
	v_max_i32_e32 v95, 0xffffffc6, v88
	v_add_u32_e32 v80, 32, v80
	v_add_u32_e32 v81, 33, v81
	v_add_u32_e32 v82, 34, v82
	v_add_u32_e32 v83, 35, v83
	v_add_u32_e32 v84, 40, v84
	v_add_u32_e32 v85, 41, v85
	v_add_u32_e32 v86, 42, v86
	v_add_u32_e32 v87, 43, v87
	v_add_u32_e32 v89, 48, v89
	v_add_u32_e32 v90, 49, v90
	v_add_u32_e32 v91, 50, v91
	v_add_u32_e32 v92, 51, v92
	v_add_u32_e32 v93, 56, v93
	v_add_u32_e32 v94, 57, v94
	v_add_u32_e32 v95, 58, v95
	v_max_i32_e32 v88, 0xffffffc5, v88
	v_min_u32_e32 v80, 0x100, v80
	v_min_u32_e32 v81, 0x100, v81
	v_min_u32_e32 v82, 0x100, v82
	v_min_u32_e32 v83, 0x100, v83
	v_min_u32_e32 v84, 0x100, v84
	v_min_u32_e32 v85, 0x100, v85
	v_min_u32_e32 v86, 0x100, v86
	v_min_u32_e32 v87, 0x100, v87
	v_min_u32_e32 v89, 0x100, v89
	v_min_u32_e32 v90, 0x100, v90
	v_min_u32_e32 v91, 0x100, v91
	v_min_u32_e32 v92, 0x100, v92
	v_min_u32_e32 v93, 0x100, v93
	v_min_u32_e32 v94, 0x100, v94
	v_min_u32_e32 v95, 0x100, v95
	v_add_u32_e32 v88, 59, v88
	v_lshl_add_u32 v80, v80, 2, s63
	v_lshl_add_u32 v81, v81, 2, s63
	v_lshl_add_u32 v82, v82, 2, s63
	v_lshl_add_u32 v83, v83, 2, s63
	v_lshl_add_u32 v84, v84, 2, s63
	v_lshl_add_u32 v85, v85, 2, s63
	v_lshl_add_u32 v86, v86, 2, s63
	v_lshl_add_u32 v87, v87, 2, s63
	v_lshl_add_u32 v89, v89, 2, s63
	v_lshl_add_u32 v90, v90, 2, s63
	v_lshl_add_u32 v91, v91, 2, s63
	v_lshl_add_u32 v92, v92, 2, s63
	v_lshl_add_u32 v93, v93, 2, s63
	v_lshl_add_u32 v94, v94, 2, s63
	v_lshl_add_u32 v95, v95, 2, s63
	v_min_u32_e32 v88, 0x100, v88
	v_mfma_f32_32x32x16_bf16 v[64:79], v[160:163], v[128:131], v[64:79]
	ds_read_b32 v80, v80
	ds_read_b32 v81, v81
	ds_read_b32 v82, v82
	ds_read_b32 v83, v83
	ds_read_b32 v84, v84
	ds_read_b32 v85, v85
	ds_read_b32 v86, v86
	ds_read_b32 v87, v87
	v_lshl_add_u32 v160, v88, 2, s63
	ds_read_b32 v88, v89
	ds_read_b32 v89, v90
	ds_read_b32 v90, v91
	ds_read_b32 v91, v92
	ds_read_b32 v92, v93
	ds_read_b32 v93, v94
	ds_read_b32 v94, v95
	ds_read_b32 v95, v160
	v_mov_b32_e32 v250, 0
	s_waitcnt lgkmcnt(0)
	v_mfma_f32_32x32x16_bf16 v[80:95], v[156:159], v[140:143], v[80:95]
	v_mfma_f32_32x32x16_bf16 v[80:95], v[152:155], v[136:139], v[80:95]
	v_mfma_f32_32x32x16_bf16 v[80:95], v[148:151], v[132:135], v[80:95]
	v_mfma_f32_32x32x16_bf16 v[80:95], v[144:147], v[128:131], v[80:95]
